# attention epilogue: output tile stored as contiguous rows (4 x 16 B per lane) through a per-wave LDS staging tile instead of 8 row-strided 8-byte stores
# speedup vs baseline: 1.0120x; 1.0120x over previous
.LBB0_169:
	v_div_scale_f32 v0, s[2:3], v234, v234, 1.0
	v_rcp_f32_e32 v1, v0
	v_div_scale_f32 v2, vcc, 1.0, v234, 1.0
	v_lshlrev_b32_e32 v96, 1, v193
	v_fma_f32 v3, -v0, v1, 1.0
	v_fmac_f32_e32 v1, v3, v1
	v_mul_f32_e32 v3, v2, v1
	v_fma_f32 v4, -v0, v3, v2
	v_fmac_f32_e32 v3, v4, v1
	v_fma_f32 v0, -v0, v3, v2
	v_div_fmas_f32 v0, v0, v1, v3
	v_div_fixup_f32 v0, v0, v234, 1.0
	s_xor_b32 s2, s11, 0x11800
	v_and_b32_e32 v10, 0x1c0, v222
	v_mul_u32_u24_e32 v10, 0x48, v10
	v_add_u32_e32 v10, s2, v10
	v_and_b32_e32 v11, 31, v222
	v_mul_u32_u24_e32 v12, 0x90, v11
	v_add3_u32 v12, v10, v12, v96
	v_and_b32_e32 v13, 63, v222
	v_lshrrev_b32_e32 v14, 3, v13
	v_and_b32_e32 v15, 7, v13
	v_mul_u32_u24_e32 v13, 0x90, v14
	v_lshl_add_u32 v13, v15, 4, v13
	v_add_u32_e32 v13, v10, v13
	v_sub_u32_e32 v14, v14, v11
	v_lshlrev_b32_e32 v14, 11, v14
	v_lshl_add_u32 v14, v15, 4, v14
	v_ashrrev_i32_e32 v15, 31, v14
	v_lshl_add_u64 v[14:15], v[200:201], 0, v[14:15]
	v_pk_mul_f32 v[4:5], v[32:33], v[0:1] op_sel_hi:[1,0]
	v_pk_mul_f32 v[6:7], v[34:35], v[0:1] op_sel_hi:[1,0]
	v_cvt_pk_bf16_f32 v4, v4, v5
	v_cvt_pk_bf16_f32 v5, v6, v7
	ds_write_b64 v12, v[4:5]
	v_pk_mul_f32 v[8:9], v[36:37], v[0:1] op_sel_hi:[1,0]
	v_pk_mul_f32 v[2:3], v[38:39], v[0:1] op_sel_hi:[1,0]
	v_cvt_pk_bf16_f32 v8, v8, v9
	v_cvt_pk_bf16_f32 v9, v2, v3
	ds_write_b64 v12, v[8:9] offset:16
	v_pk_mul_f32 v[4:5], v[40:41], v[0:1] op_sel_hi:[1,0]
	v_pk_mul_f32 v[6:7], v[42:43], v[0:1] op_sel_hi:[1,0]
	v_cvt_pk_bf16_f32 v4, v4, v5
	v_cvt_pk_bf16_f32 v5, v6, v7
	ds_write_b64 v12, v[4:5] offset:32
	v_pk_mul_f32 v[8:9], v[44:45], v[0:1] op_sel_hi:[1,0]
	v_pk_mul_f32 v[2:3], v[46:47], v[0:1] op_sel_hi:[1,0]
	v_cvt_pk_bf16_f32 v8, v8, v9
	v_cvt_pk_bf16_f32 v9, v2, v3
	ds_write_b64 v12, v[8:9] offset:48
	v_pk_mul_f32 v[4:5], v[16:17], v[0:1] op_sel_hi:[1,0]
	v_pk_mul_f32 v[6:7], v[18:19], v[0:1] op_sel_hi:[1,0]
	v_cvt_pk_bf16_f32 v4, v4, v5
	v_cvt_pk_bf16_f32 v5, v6, v7
	ds_write_b64 v12, v[4:5] offset:64
	v_pk_mul_f32 v[8:9], v[20:21], v[0:1] op_sel_hi:[1,0]
	v_pk_mul_f32 v[2:3], v[22:23], v[0:1] op_sel_hi:[1,0]
	v_cvt_pk_bf16_f32 v8, v8, v9
	v_cvt_pk_bf16_f32 v9, v2, v3
	ds_write_b64 v12, v[8:9] offset:80
	v_pk_mul_f32 v[4:5], v[24:25], v[0:1] op_sel_hi:[1,0]
	v_pk_mul_f32 v[6:7], v[26:27], v[0:1] op_sel_hi:[1,0]
	v_cvt_pk_bf16_f32 v4, v4, v5
	v_cvt_pk_bf16_f32 v5, v6, v7
	ds_write_b64 v12, v[4:5] offset:96
	v_pk_mul_f32 v[8:9], v[28:29], v[0:1] op_sel_hi:[1,0]
	v_pk_mul_f32 v[2:3], v[30:31], v[0:1] op_sel_hi:[1,0]
	v_cvt_pk_bf16_f32 v8, v8, v9
	v_cvt_pk_bf16_f32 v9, v2, v3
	ds_write_b64 v12, v[8:9] offset:112
	ds_read_b128 v[16:19], v13
	ds_read_b128 v[20:23], v13 offset:1152
	ds_read_b128 v[24:27], v13 offset:2304
	ds_read_b128 v[28:31], v13 offset:3456
	s_mov_b64 s[2:3], 0x4000
	v_lshl_add_u64 v[2:3], v[14:15], 0, s[2:3]
	s_mov_b64 s[2:3], 0x8000
	v_lshl_add_u64 v[4:5], v[14:15], 0, s[2:3]
	s_mov_b64 s[2:3], 0xc000
	v_lshl_add_u64 v[6:7], v[14:15], 0, s[2:3]
	s_waitcnt lgkmcnt(0)
	global_store_dwordx4 v[14:15], v[16:19], off sc1
	global_store_dwordx4 v[2:3], v[20:23], off sc1
	global_store_dwordx4 v[4:5], v[24:27], off sc1
	global_store_dwordx4 v[6:7], v[28:31], off sc1
	s_nop 1
	s_waitcnt lgkmcnt(0)
	s_barrier
	s_mov_b64 s[12:13], 0
